# phase 3: MLA-prep items dealt to the blocks whose nsacmp item covers the early half of the sequence (lighter) instead of blocks 256..511
# baseline (speedup 1.0000x reference)
; DI void phase_attn1(const Params& p, int L, char* smem) {
;   const int extra = (L > 0) ? CV_NC : 0;
;   for (int it = blockIdx.x; it < 1792 + extra; it += gridDim.x) {
;     if (it < 512) attn_item<2>(p, it, smem);
;     else if (it < 1024) nsacmp_item(p, L, it - 512, smem);
;     else if (it < 1536) attn_item<0>(p, it - 1024, smem);
;     else if (it < 1792) mlaprep_item(p, L, it - 1536, smem);
;     else conv_item_C(p, L, it - 1792, smem);
;   }
.LBB0_151:
	v_writelane_b32 v255, s33, 61
	s_lshr_b32 s2, s33, 9
	s_cmp_eq_u32 s2, 3
	s_cbranch_scc0 .Lp3_noswap
	s_sub_u32 s2, s33, 0x600
	s_lshr_b32 s3, s2, 6
	s_lshl_b32 s3, s3, 5
	s_bfe_u32 s33, s2, 0x10005
	s_lshl_b32 s33, s33, 8
	s_and_b32 s2, s2, 31
	s_or_b32 s2, s2, s3
	s_or_b32 s33, s33, s2
	s_addk_i32 s33, 0x600
	s_cmpk_eq_i32 s60, 0x700
	s_cbranch_scc0 .Lp3_noswap
	s_cmpk_ge_i32 s33, 0x700
	s_cbranch_scc1 .LBB0_150
